# in-projection K-loop SP2 load segments: the six LDS-DMA stage loads issued before the eight ds_read_b128 instead of after
# speedup vs baseline: 1.0086x; 1.0086x over previous
; #define PG8_STAGE(bufoff, gbase, voff) do { _Pragma("unroll") for (int _i = 0; _i < 2; ++_i) \
;         __builtin_amdgcn_global_load_lds((const unsigned*)((const char*)(gbase) + (voff)[_i]), (PG8_LAS unsigned*)(lds + (bufoff) + ldsw + _i * 8192), 16, 0, 0); } while (0)
; #define PG8_LDA(dst, b, h) do { _Pragma("unroll") for (int m = 0; m < 4; ++m) _Pragma("unroll") for (int k = 0; k < 2; ++k) dst[m][k] = *(const PG8_LAS bf16x8*)(lds + PG8_SA(b, h) + aoff + m * 2048 + k * 1024); } while (0)
; #define PG8_LDB(dst, b, h) do { _Pragma("unroll") for (int n = 0; n < 2; ++n) _Pragma("unroll") for (int k = 0; k < 2; ++k) dst[n][k] = *(const PG8_LAS bf16x8*)(lds + PG8_SB(b, h) + boff + n * 2048 + k * 1024); } while (0)
; #define PG8_MMA(ai, bj, At, Bt) do { __builtin_amdgcn_s_setprio(1); _Pragma("unroll") for (int m = 0; m < 4; ++m) _Pragma("unroll") for (int n = 0; n < 2; ++n) _Pragma("unroll") for (int k = 0; k < 2; ++k) \
;         acc[ai][bj][m][n] = __builtin_amdgcn_mfma_f32_16x16x32_bf16(Bt[n][k], At[m][k], acc[ai][bj][m][n], 0, 0, 0); __builtin_amdgcn_s_setprio(0); } while (0)
; #define PG8_WAIT_V(n) asm volatile("s_waitcnt vmcnt(" #n ")" ::: "memory")
; #define PG8_WAIT_L(n) asm volatile("s_waitcnt lgkmcnt(" #n ")" ::: "memory")
; #define PG8_BAR __builtin_amdgcn_s_barrier()
; #define PG8_SCHED __builtin_amdgcn_sched_barrier(0)
; template <class Epi, class Sched, bool ALIGN_EPI = false, bool SP2 = false>
; __device__ __forceinline__ void gemm_phase(PG8_LAS unsigned char* lds, const Gemm g, const Sched& S, const Epi& E) {
;     ...
;             PG8_LDB(B0, 0, 0); PG8_LDB(B1, 0, 1); PG8_SCHED; PG8_LDA(At, 0, 0); PG8_STAGE(PG8_SA(1, 1), a1 + hstep, voffA);
;             PG8_WAIT_V(8); PG8_WAIT_L(0); PG8_BAR; PG8_MMA(0, 0, At, B0); PG8_MMA(0, 1, At, B1); PG8_BAR; PG8_SCHED;
;             PG8_LDA(At, 0, 1); PG8_STAGE(PG8_SB(0, 0), b2, voffB); PG8_STAGE(PG8_SB(0, 1), b2 + hstep, voffB); PG8_STAGE(PG8_SA(0, 0), a2, voffA);
;             PG8_WAIT_V(8); PG8_WAIT_L(0); PG8_BAR; PG8_MMA(1, 0, At, B0); PG8_MMA(1, 1, At, B1); PG8_BAR; PG8_SCHED;
.LBB0_133:
	s_add_u32 s18, s16, 0xfffc0080
	s_addc_u32 s19, s17, -1
	s_add_i32 s41, 0, 0x10000
	s_cmp_eq_u32 s40, 12
	s_cselect_b32 s21, s1, s19
	s_cselect_b32 s20, s11, s18
	v_add_u32_e32 v156, s41, v159
	s_cselect_b32 s19, s9, s39
	s_cselect_b32 s18, s33, s38
	s_add_i32 s44, 0, 0x14000
	ds_read_b128 v[144:147], v156
	ds_read_b128 v[148:151], v156 offset:1024
	ds_read_b128 v[152:155], v156 offset:2048
	ds_read_b128 v[162:165], v156 offset:3072
	v_add_u32_e32 v156, s44, v159
	ds_read_b128 v[166:169], v156
	ds_read_b128 v[170:173], v156 offset:1024
	ds_read_b128 v[174:177], v156 offset:2048
	ds_read_b128 v[178:181], v156 offset:3072
	v_lshl_add_u64 v[156:157], s[16:17], 0, v[140:141]
	s_add_i32 m0, s24, 0xc000
	ds_read_b128 v[182:185], v161
	ds_read_b128 v[194:197], v161 offset:1024
	ds_read_b128 v[198:201], v161 offset:2048
	ds_read_b128 v[202:205], v161 offset:3072
	ds_read_b128 v[210:213], v161 offset:4096
	ds_read_b128 v[214:217], v161 offset:5120
	ds_read_b128 v[218:221], v161 offset:6144
	ds_read_b128 v[222:225], v161 offset:7168
	global_load_lds_dwordx4 v[156:157], off
	v_lshl_add_u64 v[156:157], s[16:17], 0, v[142:143]
	s_add_i32 m0, s24, 0xe000
	s_nop 0
	global_load_lds_dwordx4 v[156:157], off
	s_waitcnt vmcnt(8)
	s_waitcnt lgkmcnt(0)
	s_barrier
	s_setprio 1
	s_waitcnt lgkmcnt(0)
	v_mfma_f32_16x16x32_bf16 v[124:127], v[144:147], v[182:185], v[124:127]
	v_mfma_f32_16x16x32_bf16 v[120:123], v[152:155], v[182:185], v[120:123]
	v_mfma_f32_16x16x32_bf16 v[108:111], v[144:147], v[198:201], v[108:111]
	v_mfma_f32_16x16x32_bf16 v[104:107], v[152:155], v[198:201], v[104:107]
	v_mfma_f32_16x16x32_bf16 v[92:95], v[144:147], v[210:213], v[92:95]
	v_mfma_f32_16x16x32_bf16 v[88:91], v[152:155], v[210:213], v[88:91]
	v_mfma_f32_16x16x32_bf16 v[76:79], v[144:147], v[218:221], v[76:79]
	v_mfma_f32_16x16x32_bf16 v[72:75], v[152:155], v[218:221], v[72:75]
	v_mfma_f32_16x16x32_bf16 v[124:127], v[148:151], v[194:197], v[124:127]
	v_mfma_f32_16x16x32_bf16 v[120:123], v[162:165], v[194:197], v[120:123]
	v_mfma_f32_16x16x32_bf16 v[108:111], v[148:151], v[202:205], v[108:111]
	v_mfma_f32_16x16x32_bf16 v[104:107], v[162:165], v[202:205], v[104:107]
	v_mfma_f32_16x16x32_bf16 v[92:95], v[148:151], v[214:217], v[92:95]
	v_mfma_f32_16x16x32_bf16 v[88:91], v[162:165], v[214:217], v[88:91]
	v_mfma_f32_16x16x32_bf16 v[76:79], v[148:151], v[222:225], v[76:79]
	v_mfma_f32_16x16x32_bf16 v[72:75], v[162:165], v[222:225], v[72:75]
	s_setprio 0
	s_setprio 1
	v_mfma_f32_16x16x32_bf16 v[116:119], v[166:169], v[182:185], v[116:119]
	v_mfma_f32_16x16x32_bf16 v[112:115], v[174:177], v[182:185], v[112:115]
	v_mfma_f32_16x16x32_bf16 v[100:103], v[166:169], v[198:201], v[100:103]
	v_mfma_f32_16x16x32_bf16 v[96:99], v[174:177], v[198:201], v[96:99]
	v_mfma_f32_16x16x32_bf16 v[84:87], v[166:169], v[210:213], v[84:87]
	v_mfma_f32_16x16x32_bf16 v[80:83], v[174:177], v[210:213], v[80:83]
	v_mfma_f32_16x16x32_bf16 v[68:71], v[166:169], v[218:221], v[68:71]
	v_mfma_f32_16x16x32_bf16 v[64:67], v[174:177], v[218:221], v[64:67]
	v_mfma_f32_16x16x32_bf16 v[116:119], v[170:173], v[194:197], v[116:119]
	v_mfma_f32_16x16x32_bf16 v[112:115], v[178:181], v[194:197], v[112:115]
	v_mfma_f32_16x16x32_bf16 v[100:103], v[170:173], v[202:205], v[100:103]
	v_mfma_f32_16x16x32_bf16 v[96:99], v[178:181], v[202:205], v[96:99]
	v_mfma_f32_16x16x32_bf16 v[84:87], v[170:173], v[214:217], v[84:87]
	v_mfma_f32_16x16x32_bf16 v[80:83], v[178:181], v[214:217], v[80:83]
	v_mfma_f32_16x16x32_bf16 v[68:71], v[170:173], v[222:225], v[68:71]
	v_mfma_f32_16x16x32_bf16 v[64:67], v[178:181], v[222:225], v[64:67]
	s_setprio 0
	s_barrier
	s_add_i32 s41, s41, s23
	v_lshl_add_u64 v[156:157], s[18:19], 0, v[130:131]
	s_mov_b32 m0, s41
	s_nop 0
	global_load_lds_dwordx4 v[156:157], off
	s_add_i32 m0, s41, 0x2000
	s_add_u32 s42, s18, 0x40000
	v_lshl_add_u64 v[186:187], s[18:19], 0, v[134:135]
	s_addc_u32 s43, s19, 0
	s_add_i32 s41, s44, s23
	global_load_lds_dwordx4 v[186:187], off
	v_lshl_add_u64 v[190:191], s[42:43], 0, v[130:131]
	s_mov_b32 m0, s41
	v_lshl_add_u64 v[226:227], s[20:21], 0, v[132:133]
	global_load_lds_dwordx4 v[190:191], off
	v_lshl_add_u64 v[190:191], s[42:43], 0, v[134:135]
	s_add_i32 m0, s41, 0x2000
	s_nop 0
	global_load_lds_dwordx4 v[190:191], off
	v_lshl_add_u64 v[190:191], s[20:21], 0, v[128:129]
	s_mov_b32 m0, s24
	s_nop 0
	global_load_lds_dwordx4 v[190:191], off
	s_mov_b32 m0, s25
	s_nop 0
	global_load_lds_dwordx4 v[226:227], off
	ds_read_b128 v[182:185], v161 offset:16384
	ds_read_b128 v[194:197], v161 offset:17408
	ds_read_b128 v[198:201], v161 offset:18432
	ds_read_b128 v[202:205], v161 offset:19456
	ds_read_b128 v[210:213], v161 offset:20480
	ds_read_b128 v[214:217], v161 offset:21504
	ds_read_b128 v[218:221], v161 offset:22528
	ds_read_b128 v[222:225], v161 offset:23552
	s_waitcnt vmcnt(8)
	s_waitcnt lgkmcnt(0)
	s_barrier
; #define PG8_STAGE(bufoff, gbase, voff) do { _Pragma("unroll") for (int _i = 0; _i < 2; ++_i) \
;         __builtin_amdgcn_global_load_lds((const unsigned*)((const char*)(gbase) + (voff)[_i]), (PG8_LAS unsigned*)(lds + (bufoff) + ldsw + _i * 8192), 16, 0, 0); } while (0)
; #define PG8_LDA(dst, b, h) do { _Pragma("unroll") for (int m = 0; m < 4; ++m) _Pragma("unroll") for (int k = 0; k < 2; ++k) dst[m][k] = *(const PG8_LAS bf16x8*)(lds + PG8_SA(b, h) + aoff + m * 2048 + k * 1024); } while (0)
; #define PG8_LDB(dst, b, h) do { _Pragma("unroll") for (int n = 0; n < 2; ++n) _Pragma("unroll") for (int k = 0; k < 2; ++k) dst[n][k] = *(const PG8_LAS bf16x8*)(lds + PG8_SB(b, h) + boff + n * 2048 + k * 1024); } while (0)
; #define PG8_MMA(ai, bj, At, Bt) do { __builtin_amdgcn_s_setprio(1); _Pragma("unroll") for (int m = 0; m < 4; ++m) _Pragma("unroll") for (int n = 0; n < 2; ++n) _Pragma("unroll") for (int k = 0; k < 2; ++k) \
;         acc[ai][bj][m][n] = __builtin_amdgcn_mfma_f32_16x16x32_bf16(Bt[n][k], At[m][k], acc[ai][bj][m][n], 0, 0, 0); __builtin_amdgcn_s_setprio(0); } while (0)
; #define PG8_WAIT_V(n) asm volatile("s_waitcnt vmcnt(" #n ")" ::: "memory")
; #define PG8_WAIT_L(n) asm volatile("s_waitcnt lgkmcnt(" #n ")" ::: "memory")
; #define PG8_BAR __builtin_amdgcn_s_barrier()
; #define PG8_SCHED __builtin_amdgcn_sched_barrier(0)
; template <class Epi, class Sched, bool ALIGN_EPI = false, bool SP2 = false>
; __device__ __forceinline__ void gemm_phase(PG8_LAS unsigned char* lds, const Gemm g, const Sched& S, const Epi& E) {
;     ...
;             PG8_WAIT_V(8); PG8_WAIT_L(0); PG8_BAR; PG8_MMA(1, 0, At, B0); PG8_MMA(1, 1, At, B1); PG8_BAR; PG8_SCHED;
;             PG8_LDB(B0, 1, 0); PG8_LDB(B1, 1, 1); PG8_SCHED; PG8_LDA(At, 1, 0); PG8_STAGE(PG8_SA(0, 1), a2 + hstep, voffA);
;             PG8_WAIT_V(8); PG8_WAIT_L(0); PG8_BAR; PG8_MMA(0, 0, At, B0); PG8_MMA(0, 1, At, B1); PG8_BAR; PG8_SCHED;
	s_setprio 1
	s_waitcnt lgkmcnt(0)
	v_mfma_f32_16x16x32_bf16 v[60:63], v[144:147], v[182:185], v[60:63]
	v_mfma_f32_16x16x32_bf16 v[56:59], v[152:155], v[182:185], v[56:59]
	v_mfma_f32_16x16x32_bf16 v[44:47], v[144:147], v[198:201], v[44:47]
	v_mfma_f32_16x16x32_bf16 v[40:43], v[152:155], v[198:201], v[40:43]
	v_mfma_f32_16x16x32_bf16 v[28:31], v[144:147], v[210:213], v[28:31]
	v_mfma_f32_16x16x32_bf16 v[24:27], v[152:155], v[210:213], v[24:27]
	v_mfma_f32_16x16x32_bf16 v[12:15], v[144:147], v[218:221], v[12:15]
	v_mfma_f32_16x16x32_bf16 v[8:11], v[152:155], v[218:221], v[8:11]
	v_mfma_f32_16x16x32_bf16 v[60:63], v[148:151], v[194:197], v[60:63]
	v_mfma_f32_16x16x32_bf16 v[56:59], v[162:165], v[194:197], v[56:59]
	v_mfma_f32_16x16x32_bf16 v[44:47], v[148:151], v[202:205], v[44:47]
	v_mfma_f32_16x16x32_bf16 v[40:43], v[162:165], v[202:205], v[40:43]
	v_mfma_f32_16x16x32_bf16 v[28:31], v[148:151], v[214:217], v[28:31]
	v_mfma_f32_16x16x32_bf16 v[24:27], v[162:165], v[214:217], v[24:27]
	v_mfma_f32_16x16x32_bf16 v[12:15], v[148:151], v[222:225], v[12:15]
	v_mfma_f32_16x16x32_bf16 v[8:11], v[162:165], v[222:225], v[8:11]
	s_setprio 0
	s_setprio 1
	v_mfma_f32_16x16x32_bf16 v[52:55], v[166:169], v[182:185], v[52:55]
	v_mfma_f32_16x16x32_bf16 v[48:51], v[174:177], v[182:185], v[48:51]
	v_mfma_f32_16x16x32_bf16 v[36:39], v[166:169], v[198:201], v[36:39]
	v_mfma_f32_16x16x32_bf16 v[32:35], v[174:177], v[198:201], v[32:35]
	v_mfma_f32_16x16x32_bf16 v[20:23], v[166:169], v[210:213], v[20:23]
	v_mfma_f32_16x16x32_bf16 v[16:19], v[174:177], v[210:213], v[16:19]
	v_mfma_f32_16x16x32_bf16 v[4:7], v[166:169], v[218:221], v[4:7]
	v_mfma_f32_16x16x32_bf16 v[0:3], v[174:177], v[218:221], v[0:3]
	v_mfma_f32_16x16x32_bf16 v[52:55], v[170:173], v[194:197], v[52:55]
	v_mfma_f32_16x16x32_bf16 v[48:51], v[178:181], v[194:197], v[48:51]
	v_mfma_f32_16x16x32_bf16 v[36:39], v[170:173], v[202:205], v[36:39]
	v_mfma_f32_16x16x32_bf16 v[32:35], v[178:181], v[202:205], v[32:35]
	v_mfma_f32_16x16x32_bf16 v[20:23], v[170:173], v[214:217], v[20:23]
	v_mfma_f32_16x16x32_bf16 v[16:19], v[178:181], v[214:217], v[16:19]
	v_mfma_f32_16x16x32_bf16 v[4:7], v[170:173], v[222:225], v[4:7]
	v_mfma_f32_16x16x32_bf16 v[0:3], v[178:181], v[222:225], v[0:3]
	s_setprio 0
	s_barrier
	s_add_i32 s41, 0, 0x18000
	s_add_i32 s42, 0, 0x1c000
	v_add_u32_e32 v162, s41, v159
	v_add_u32_e32 v178, s42, v159
	ds_read_b128 v[144:147], v162
	ds_read_b128 v[148:151], v162 offset:1024
	ds_read_b128 v[152:155], v162 offset:2048
	ds_read_b128 v[162:165], v162 offset:3072
	ds_read_b128 v[166:169], v178
	ds_read_b128 v[170:173], v178 offset:1024
	ds_read_b128 v[174:177], v178 offset:2048
	ds_read_b128 v[178:181], v178 offset:3072
	s_add_u32 s20, s20, 0x40000
	s_addc_u32 s21, s21, 0
	s_mov_b32 m0, s26
	v_lshl_add_u64 v[228:229], s[20:21], 0, v[128:129]
	ds_read_b128 v[182:185], v161 offset:32768
	ds_read_b128 v[194:197], v161 offset:33792
	ds_read_b128 v[198:201], v161 offset:34816
	ds_read_b128 v[202:205], v161 offset:35840
	ds_read_b128 v[210:213], v161 offset:36864
	ds_read_b128 v[214:217], v161 offset:37888
	ds_read_b128 v[218:221], v161 offset:38912
	ds_read_b128 v[222:225], v161 offset:39936
	global_load_lds_dwordx4 v[228:229], off
	v_lshl_add_u64 v[228:229], s[20:21], 0, v[132:133]
	s_mov_b32 m0, s27
	s_nop 0
	global_load_lds_dwordx4 v[228:229], off
	s_waitcnt vmcnt(8)
	s_waitcnt lgkmcnt(0)
	s_barrier
	s_setprio 1
	s_waitcnt lgkmcnt(0)
	v_mfma_f32_16x16x32_bf16 v[124:127], v[144:147], v[182:185], v[124:127]
	v_mfma_f32_16x16x32_bf16 v[120:123], v[152:155], v[182:185], v[120:123]
	v_mfma_f32_16x16x32_bf16 v[108:111], v[144:147], v[198:201], v[108:111]
	v_mfma_f32_16x16x32_bf16 v[104:107], v[152:155], v[198:201], v[104:107]
	v_mfma_f32_16x16x32_bf16 v[92:95], v[144:147], v[210:213], v[92:95]
	v_mfma_f32_16x16x32_bf16 v[88:91], v[152:155], v[210:213], v[88:91]
	v_mfma_f32_16x16x32_bf16 v[76:79], v[144:147], v[218:221], v[76:79]
	v_mfma_f32_16x16x32_bf16 v[72:75], v[152:155], v[218:221], v[72:75]
	v_mfma_f32_16x16x32_bf16 v[124:127], v[148:151], v[194:197], v[124:127]
	v_mfma_f32_16x16x32_bf16 v[120:123], v[162:165], v[194:197], v[120:123]
	v_mfma_f32_16x16x32_bf16 v[108:111], v[148:151], v[202:205], v[108:111]
	v_mfma_f32_16x16x32_bf16 v[104:107], v[162:165], v[202:205], v[104:107]
	v_mfma_f32_16x16x32_bf16 v[92:95], v[148:151], v[214:217], v[92:95]
	v_mfma_f32_16x16x32_bf16 v[88:91], v[162:165], v[214:217], v[88:91]
	v_mfma_f32_16x16x32_bf16 v[76:79], v[148:151], v[222:225], v[76:79]
	v_mfma_f32_16x16x32_bf16 v[72:75], v[162:165], v[222:225], v[72:75]
	s_setprio 0
	s_setprio 1
	v_mfma_f32_16x16x32_bf16 v[116:119], v[166:169], v[182:185], v[116:119]
	v_mfma_f32_16x16x32_bf16 v[112:115], v[174:177], v[182:185], v[112:115]
	v_mfma_f32_16x16x32_bf16 v[100:103], v[166:169], v[198:201], v[100:103]
	v_mfma_f32_16x16x32_bf16 v[96:99], v[174:177], v[198:201], v[96:99]
	v_mfma_f32_16x16x32_bf16 v[84:87], v[166:169], v[210:213], v[84:87]
	v_mfma_f32_16x16x32_bf16 v[80:83], v[174:177], v[210:213], v[80:83]
	v_mfma_f32_16x16x32_bf16 v[68:71], v[166:169], v[218:221], v[68:71]
	v_mfma_f32_16x16x32_bf16 v[64:67], v[174:177], v[218:221], v[64:67]
	v_mfma_f32_16x16x32_bf16 v[116:119], v[170:173], v[194:197], v[116:119]
	v_mfma_f32_16x16x32_bf16 v[112:115], v[178:181], v[194:197], v[112:115]
	v_mfma_f32_16x16x32_bf16 v[100:103], v[170:173], v[202:205], v[100:103]
	v_mfma_f32_16x16x32_bf16 v[96:99], v[178:181], v[202:205], v[96:99]
	v_mfma_f32_16x16x32_bf16 v[84:87], v[170:173], v[214:217], v[84:87]
	v_mfma_f32_16x16x32_bf16 v[80:83], v[178:181], v[214:217], v[80:83]
	v_mfma_f32_16x16x32_bf16 v[68:71], v[170:173], v[222:225], v[68:71]
	v_mfma_f32_16x16x32_bf16 v[64:67], v[178:181], v[222:225], v[64:67]
	s_setprio 0
	s_barrier
; #define PG8_STAGE(bufoff, gbase, voff) do { _Pragma("unroll") for (int _i = 0; _i < 2; ++_i) \
;         __builtin_amdgcn_global_load_lds((const unsigned*)((const char*)(gbase) + (voff)[_i]), (PG8_LAS unsigned*)(lds + (bufoff) + ldsw + _i * 8192), 16, 0, 0); } while (0)
; #define PG8_LDA(dst, b, h) do { _Pragma("unroll") for (int m = 0; m < 4; ++m) _Pragma("unroll") for (int k = 0; k < 2; ++k) dst[m][k] = *(const PG8_LAS bf16x8*)(lds + PG8_SA(b, h) + aoff + m * 2048 + k * 1024); } while (0)
; #define PG8_MMA(ai, bj, At, Bt) do { __builtin_amdgcn_s_setprio(1); _Pragma("unroll") for (int m = 0; m < 4; ++m) _Pragma("unroll") for (int n = 0; n < 2; ++n) _Pragma("unroll") for (int k = 0; k < 2; ++k) \
;         acc[ai][bj][m][n] = __builtin_amdgcn_mfma_f32_16x16x32_bf16(Bt[n][k], At[m][k], acc[ai][bj][m][n], 0, 0, 0); __builtin_amdgcn_s_setprio(0); } while (0)
; #define PG8_WAIT_V(n) asm volatile("s_waitcnt vmcnt(" #n ")" ::: "memory")
; #define PG8_WAIT_L(n) asm volatile("s_waitcnt lgkmcnt(" #n ")" ::: "memory")
; #define PG8_BAR __builtin_amdgcn_s_barrier()
; #define PG8_SCHED __builtin_amdgcn_sched_barrier(0)
; template <class Epi, class Sched, bool ALIGN_EPI = false, bool SP2 = false>
; __device__ __forceinline__ void gemm_phase(PG8_LAS unsigned char* lds, const Gemm g, const Sched& S, const Epi& E) {
;     ...
;             PG8_LDA(At, 1, 1); PG8_STAGE(PG8_SB(1, 0), b3, voffB); PG8_STAGE(PG8_SB(1, 1), b3 + hstep, voffB); PG8_STAGE(PG8_SA(1, 0), a3, voffA);
;             PG8_WAIT_V(8); PG8_WAIT_L(0); PG8_BAR; PG8_MMA(1, 0, At, B0); PG8_MMA(1, 1, At, B1); PG8_BAR; PG8_SCHED;
	s_add_i32 s20, s41, s23
	v_lshl_add_u64 v[156:157], v[156:157], 0, s[46:47]
	s_mov_b32 m0, s20
	s_nop 0
	global_load_lds_dwordx4 v[156:157], off
	s_add_i32 m0, s20, 0x2000
	s_add_u32 s18, s18, 0x40080
	v_lshl_add_u64 v[156:157], v[186:187], 0, s[46:47]
	s_addc_u32 s19, s19, 0
	s_add_i32 s20, s42, s23
	global_load_lds_dwordx4 v[156:157], off
	v_lshl_add_u64 v[156:157], s[18:19], 0, v[130:131]
	s_mov_b32 m0, s20
	s_nop 0
	global_load_lds_dwordx4 v[156:157], off
	v_lshl_add_u64 v[156:157], s[18:19], 0, v[134:135]
	s_add_i32 m0, s20, 0x2000
	s_nop 0
	global_load_lds_dwordx4 v[156:157], off
	v_lshl_add_u64 v[156:157], v[190:191], 0, s[46:47]
	s_mov_b32 m0, s30
	s_nop 0
	global_load_lds_dwordx4 v[156:157], off
	v_lshl_add_u64 v[156:157], v[226:227], 0, s[46:47]
	s_mov_b32 m0, s31
	s_nop 0
	global_load_lds_dwordx4 v[156:157], off
	ds_read_b128 v[182:185], v161 offset:49152
	ds_read_b128 v[194:197], v161 offset:50176
	ds_read_b128 v[198:201], v161 offset:51200
	ds_read_b128 v[202:205], v161 offset:52224
	ds_read_b128 v[210:213], v161 offset:53248
	ds_read_b128 v[214:217], v161 offset:54272
	ds_read_b128 v[218:221], v161 offset:55296
	ds_read_b128 v[222:225], v161 offset:56320
	s_waitcnt vmcnt(8)
	s_waitcnt lgkmcnt(0)
	s_barrier
	s_setprio 1
	s_waitcnt lgkmcnt(0)
	v_mfma_f32_16x16x32_bf16 v[60:63], v[144:147], v[182:185], v[60:63]
	v_mfma_f32_16x16x32_bf16 v[56:59], v[152:155], v[182:185], v[56:59]
	v_mfma_f32_16x16x32_bf16 v[44:47], v[144:147], v[198:201], v[44:47]
	v_mfma_f32_16x16x32_bf16 v[40:43], v[152:155], v[198:201], v[40:43]
	v_mfma_f32_16x16x32_bf16 v[28:31], v[144:147], v[210:213], v[28:31]
	v_mfma_f32_16x16x32_bf16 v[24:27], v[152:155], v[210:213], v[24:27]
	v_mfma_f32_16x16x32_bf16 v[12:15], v[144:147], v[218:221], v[12:15]
	v_mfma_f32_16x16x32_bf16 v[8:11], v[152:155], v[218:221], v[8:11]
	v_mfma_f32_16x16x32_bf16 v[60:63], v[148:151], v[194:197], v[60:63]
	v_mfma_f32_16x16x32_bf16 v[56:59], v[162:165], v[194:197], v[56:59]
	v_mfma_f32_16x16x32_bf16 v[44:47], v[148:151], v[202:205], v[44:47]
	v_mfma_f32_16x16x32_bf16 v[40:43], v[162:165], v[202:205], v[40:43]
	v_mfma_f32_16x16x32_bf16 v[28:31], v[148:151], v[214:217], v[28:31]
	v_mfma_f32_16x16x32_bf16 v[24:27], v[162:165], v[214:217], v[24:27]
	v_mfma_f32_16x16x32_bf16 v[12:15], v[148:151], v[222:225], v[12:15]
	v_mfma_f32_16x16x32_bf16 v[8:11], v[162:165], v[222:225], v[8:11]
	s_setprio 0
	s_setprio 1
	v_mfma_f32_16x16x32_bf16 v[52:55], v[166:169], v[182:185], v[52:55]
	v_mfma_f32_16x16x32_bf16 v[48:51], v[174:177], v[182:185], v[48:51]
	v_mfma_f32_16x16x32_bf16 v[36:39], v[166:169], v[198:201], v[36:39]
	v_mfma_f32_16x16x32_bf16 v[32:35], v[174:177], v[198:201], v[32:35]
	v_mfma_f32_16x16x32_bf16 v[20:23], v[166:169], v[210:213], v[20:23]
	v_mfma_f32_16x16x32_bf16 v[16:19], v[174:177], v[210:213], v[16:19]
	v_mfma_f32_16x16x32_bf16 v[4:7], v[166:169], v[218:221], v[4:7]
	v_mfma_f32_16x16x32_bf16 v[0:3], v[174:177], v[218:221], v[0:3]
	v_mfma_f32_16x16x32_bf16 v[52:55], v[170:173], v[194:197], v[52:55]
	v_mfma_f32_16x16x32_bf16 v[48:51], v[178:181], v[194:197], v[48:51]
	v_mfma_f32_16x16x32_bf16 v[36:39], v[170:173], v[202:205], v[36:39]
	v_mfma_f32_16x16x32_bf16 v[32:35], v[178:181], v[202:205], v[32:35]
	v_mfma_f32_16x16x32_bf16 v[20:23], v[170:173], v[214:217], v[20:23]
	v_mfma_f32_16x16x32_bf16 v[16:19], v[178:181], v[214:217], v[16:19]
	v_mfma_f32_16x16x32_bf16 v[4:7], v[170:173], v[222:225], v[4:7]
	v_mfma_f32_16x16x32_bf16 v[0:3], v[178:181], v[222:225], v[0:3]
	s_setprio 0
	s_barrier
	s_add_i32 s40, s40, 2
	s_add_u32 s16, s16, 0x100
	s_addc_u32 s17, s17, 0
	s_add_u32 s38, s38, 0x100
	s_addc_u32 s39, s39, 0
	s_cmp_gt_u32 s40, 13
	s_cbranch_scc0 .LBB0_133
	s_and_b64 vcc, exec, s[6:7]
	s_cbranch_vccz .LBB0_136
	s_barrier
